# final-norm and input-conversion row loops: the loads of a row issued as one batch
# speedup vs baseline: 1.0394x; 1.0019x over previous
.LBB0_69:
	global_load_dwordx4 v[44:47], v[18:19], off
	global_load_dwordx4 v[40:43], v[18:19], off offset:1024
	v_mov_b64_e32 v[32:33], s[6:7]
	flat_load_dwordx4 v[20:23], v[32:33]
	flat_load_dwordx4 v[24:27], v[32:33] offset:16
	flat_load_dwordx4 v[28:31], v[32:33] offset:32
	s_nop 0
	flat_load_dwordx4 v[32:35], v[32:33] offset:48
	s_add_i32 s4, s4, s80
	s_add_u32 s6, s6, s78
	s_addc_u32 s7, s7, s79
	s_cmpk_lt_i32 s4, 0x4400
	s_waitcnt vmcnt(0) lgkmcnt(0)
	v_mov_b32_e32 v36, v21
	v_mov_b32_e32 v37, v22
	v_mov_b32_e32 v21, v23
	v_mov_b32_e32 v22, v25
	v_mov_b32_e32 v23, v26
	v_mov_b32_e32 v25, v27
	v_pk_add_f32 v[20:21], v[36:37], v[20:21]
	v_pk_add_f32 v[22:23], v[22:23], v[24:25]
	v_pk_add_f32 v[20:21], v[20:21], v[20:21] op_sel:[0,1] op_sel_hi:[1,0]
	v_pk_add_f32 v[22:23], v[22:23], v[22:23] op_sel:[0,1] op_sel_hi:[1,0]
	v_add_f32_e32 v24, v28, v29
	v_add_f32_e32 v26, v30, v31
	v_mov_b32_e32 v21, v32
	v_mov_b32_e32 v23, v33
	v_mov_b32_e32 v25, v34
	v_mov_b32_e32 v27, v35
	v_pk_add_f32 v[20:21], v[20:21], v[22:23]
	v_pk_add_f32 v[22:23], v[24:25], v[26:27]
	s_nop 0
	v_pk_add_f32 v[20:21], v[20:21], v[22:23]
	v_mov_b32_e32 v22, v44
	v_mov_b32_e32 v23, v45
	v_mov_b32_e32 v24, v46
	v_mov_b32_e32 v25, v47
	v_add_f32_e32 v20, v20, v21
	v_fmamk_f32 v20, v20, 0x3a800000, v183
	v_rsq_f32_e32 v20, v20
	v_lshlrev_b32_e32 v26, 16, v22
	v_and_b32_e32 v27, 0xffff0000, v22
	v_lshlrev_b32_e32 v22, 16, v23
	v_and_b32_e32 v23, 0xffff0000, v23
	v_pk_mul_f32 v[26:27], v[20:21], v[26:27] op_sel_hi:[0,1]
	v_pk_mul_f32 v[22:23], v[20:21], v[22:23] op_sel_hi:[0,1]
	v_lshlrev_b32_e32 v28, 16, v24
	v_and_b32_e32 v29, 0xffff0000, v24
	v_lshlrev_b32_e32 v30, 16, v25
	v_and_b32_e32 v31, 0xffff0000, v25
	v_pk_mul_f32 v[24:25], v[6:7], v[22:23]
	v_pk_mul_f32 v[22:23], v[4:5], v[26:27]
	flat_store_dwordx4 v[16:17], v[22:25] nt
	s_nop 1
	v_pk_mul_f32 v[22:23], v[20:21], v[28:29] op_sel_hi:[0,1]
	v_pk_mul_f32 v[24:25], v[20:21], v[30:31] op_sel_hi:[0,1]
	v_pk_mul_f32 v[24:25], v[2:3], v[24:25]
	v_pk_mul_f32 v[22:23], v[0:1], v[22:23]
	flat_store_dwordx4 v[16:17], v[22:25] offset:16 nt
	s_nop 1
	v_mov_b32_e32 v22, v40
	v_mov_b32_e32 v23, v41
	v_mov_b32_e32 v24, v42
	v_mov_b32_e32 v25, v43
	v_lshl_add_u64 v[18:19], v[18:19], 0, s[76:77]
	v_lshlrev_b32_e32 v26, 16, v22
	v_and_b32_e32 v27, 0xffff0000, v22
	v_lshlrev_b32_e32 v22, 16, v23
	v_and_b32_e32 v23, 0xffff0000, v23
	v_pk_mul_f32 v[26:27], v[20:21], v[26:27] op_sel_hi:[0,1]
	v_pk_mul_f32 v[22:23], v[20:21], v[22:23] op_sel_hi:[0,1]
	v_lshlrev_b32_e32 v28, 16, v24
	v_and_b32_e32 v29, 0xffff0000, v24
	v_lshlrev_b32_e32 v30, 16, v25
	v_and_b32_e32 v31, 0xffff0000, v25
	v_pk_mul_f32 v[24:25], v[14:15], v[22:23]
	v_pk_mul_f32 v[22:23], v[12:13], v[26:27]
	flat_store_dwordx4 v[16:17], v[22:25] offset:2048 nt
	s_nop 1
	v_pk_mul_f32 v[24:25], v[20:21], v[28:29] op_sel_hi:[0,1]
	v_pk_mul_f32 v[20:21], v[20:21], v[30:31] op_sel_hi:[0,1]
	v_pk_mul_f32 v[22:23], v[10:11], v[20:21]
	v_pk_mul_f32 v[20:21], v[8:9], v[24:25]
	flat_store_dwordx4 v[16:17], v[20:23] offset:2064 nt
	v_lshl_add_u64 v[16:17], v[16:17], 0, s[8:9]
	s_cbranch_scc1 .LBB0_69

.LBB0_438:
	global_load_dwordx4 v[14:17], v0, s[16:17] offset:16 nt
	global_load_dwordx4 v[18:21], v0, s[16:17] nt
	global_load_dwordx4 v[76:79], v0, s[16:17] offset:2064 nt
	global_load_dwordx4 v[80:83], v0, s[16:17] offset:2048 nt
	s_lshl_b64 s[18:19], s[14:15], 11
	v_lshl_add_u64 v[22:23], v[6:7], 0, s[18:19]
	s_waitcnt vmcnt(0)
	v_mul_f32_e32 v3, v19, v19
	s_waitcnt lgkmcnt(0)
	v_mul_f32_e32 v13, v21, v21
	v_fmac_f32_e32 v3, v18, v18
	v_fmac_f32_e32 v13, v20, v20
	v_add_f32_e32 v3, v3, v13
	v_mul_f32_e32 v13, v15, v15
	v_fmac_f32_e32 v13, v14, v14
	v_cvt_pk_bf16_f32 v18, v18, v19
	v_cvt_pk_bf16_f32 v19, v20, v21
	v_cvt_pk_bf16_f32 v20, v14, v15
	v_cvt_pk_bf16_f32 v21, v16, v17
	v_add_f32_e32 v3, v3, v13
	v_mul_f32_e32 v13, v17, v17
	flat_store_dwordx4 v[22:23], v[18:21]
	v_fmac_f32_e32 v13, v16, v16
	v_mov_b32_e32 v14, v76
	v_mov_b32_e32 v15, v77
	v_mov_b32_e32 v16, v78
	v_mov_b32_e32 v17, v79
	v_mov_b32_e32 v18, v80
	v_mov_b32_e32 v19, v81
	v_mov_b32_e32 v20, v82
	v_mov_b32_e32 v21, v83
	v_add_f32_e32 v3, v13, v3
	v_mul_f32_e32 v13, v19, v19
	v_mul_f32_e32 v24, v21, v21
	v_fmac_f32_e32 v13, v18, v18
	v_fmac_f32_e32 v24, v20, v20
	v_add_f32_e32 v13, v13, v24
	v_mul_f32_e32 v24, v15, v15
	v_fmac_f32_e32 v24, v14, v14
	v_add_f32_e32 v13, v13, v24
	v_mul_f32_e32 v24, v17, v17
	v_fmac_f32_e32 v24, v16, v16
	v_add_f32_e32 v13, v24, v13
	v_add_f32_e32 v3, v3, v13
	ds_bpermute_b32 v13, v1, v3
	v_cvt_pk_bf16_f32 v18, v18, v19
	v_cvt_pk_bf16_f32 v19, v20, v21
	v_cvt_pk_bf16_f32 v20, v14, v15
	v_cvt_pk_bf16_f32 v21, v16, v17
	s_waitcnt lgkmcnt(0)
	v_add_f32_e32 v3, v3, v13
	ds_bpermute_b32 v13, v8, v3
	flat_store_dwordx4 v[22:23], v[18:21] offset:1024
	s_waitcnt lgkmcnt(0)
	v_add_f32_e32 v3, v3, v13
	ds_bpermute_b32 v13, v9, v3
	s_waitcnt lgkmcnt(0)
	v_add_f32_e32 v3, v3, v13
	ds_bpermute_b32 v13, v10, v3
	s_waitcnt lgkmcnt(0)
	v_add_f32_e32 v3, v3, v13
	ds_bpermute_b32 v13, v11, v3
	s_waitcnt lgkmcnt(0)
	v_add_f32_e32 v3, v3, v13
	ds_bpermute_b32 v13, v12, v3
	s_and_saveexec_b64 s[16:17], vcc
	s_cbranch_execz .LBB0_435
	s_waitcnt lgkmcnt(0)
	v_add_f32_e32 v3, v3, v13
	s_lshl_b64 s[14:15], s[14:15], 6
	v_cndmask_b32_e64 v3, 0, v3, s[4:5]
	v_lshl_add_u64 v[14:15], v[4:5], 0, s[14:15]
	flat_store_dword v[14:15], v3
	s_branch .LBB0_435
